# ph10 mla_post: rope value load hoisted to the top of the row iteration, counted wait at its use (was a per-row vmcnt(0) round trip)
# baseline (speedup 1.0000x reference)
.LBB0_345:
	s_or_b64 exec, exec, s[18:19]
	v_and_b32_e32 v102, 0xffe0, v73
	v_or_b32_e32 v102, v102, v66
	v_lshlrev_b32_e32 v102, 3, v102
	global_load_dwordx2 v[100:101], v102, s[2:3]
	v_lshl_add_u64 v[62:63], v[52:53], 0, s[36:37]
	s_movk_i32 s17, 0x4fff
	v_cmp_lt_i32_e32 vcc, s17, v62
	s_and_saveexec_b64 s[18:19], vcc
	s_xor_b64 s[18:19], exec, s[18:19]
	s_cbranch_execz .LBB0_349
	v_add_u32_e32 v0, 0xffffb000, v62
	v_lshrrev_b32_e32 v0, 8, v0
	v_mul_u32_u24_e32 v0, 0x900, v0
	v_and_or_b32 v0, v62, s65, v0
	v_add_u32_e32 v0, 0x1800, v0
	v_lshlrev_b64 v[16:17], 9, v[0:1]
	v_lshl_add_u64 v[16:17], v[40:41], 0, v[16:17]
	v_cvt_pk_bf16_f32 v14, v22, v23
	v_cvt_pk_bf16_f32 v15, v24, v25
	global_store_dwordx2 v[16:17], v[14:15], off
	s_and_saveexec_b64 s[44:45], s[42:43]
	s_cbranch_execz .LBB0_348
	v_lshlrev_b64 v[14:15], 7, v[0:1]
	v_lshl_add_u64 v[14:15], v[46:47], 0, v[14:15]
	v_cvt_pk_bf16_f32 v0, v50, v51
	global_store_dword v[14:15], v0, off

.LBB0_354:
	s_or_b64 exec, exec, s[18:19]
	s_and_saveexec_b64 s[18:19], s[42:43]
	s_cbranch_execz .LBB0_337
	s_and_saveexec_b64 s[22:23], vcc
	s_xor_b64 s[44:45], exec, s[22:23]
	s_cbranch_execz .LBB0_357
	s_mov_b32 s17, 0xffe0
	s_waitcnt vmcnt(3)
	v_mov_b64_e32 v[16:17], v[100:101]
	v_pk_mul_f32 v[20:21], v[50:51], v[16:17] op_sel:[1,1] op_sel_hi:[1,0]
	s_nop 0
	v_pk_fma_f32 v[14:15], v[50:51], v[16:17], v[20:21] neg_lo:[0,0,1] neg_hi:[0,0,1]
	v_pk_fma_f32 v[16:17], v[50:51], v[16:17], v[20:21] op_sel_hi:[0,1,1]
	v_mov_b32_e32 v15, v17
